# attention: cross-half row-max exchange via v_permlane32_swap instead of ds_bpermute round trip (2 sites per kt)
# speedup vs baseline: 1.0201x; 1.0046x over previous
; __device__ __forceinline__ void attn_mfma(PP p, unsigned char* shm, int wv) {
;     ...
;                     float mx = s[0];
; #pragma unroll
;                     for (int i = 1; i < 16; ++i) mx = fmaxf(mx, s[i]);
;                     mx = fmaxf(mx, __shfl_xor(mx, 32));
;                     const float mnew = fmaxf(mrun[qi], mx * SC2);
;                     if (__builtin_amdgcn_ballot_w64(mnew > mrun[qi]) != 0ull) {
;                         const float alpha = __builtin_amdgcn_exp2f(mrun[qi] - mnew);
;                         lrun[qi] *= alpha;
; #pragma unroll
;                         for (int db = 0; db < 2; ++db)
; #pragma unroll
;                             for (int i = 0; i < 16; ++i) oacc[db][qi][i] *= alpha;
;                         mrun[qi] = mnew;
;                     }
.LBB0_472:
	s_nop 1
	v_max_f32_e32 v203, v67, v67
	v_max_f32_e32 v204, v66, v66
	v_max_f32_e32 v203, v204, v203
	v_max3_f32 v203, v203, v68, v69
	v_max3_f32 v203, v203, v70, v71
	v_max3_f32 v203, v203, v72, v73
	v_max3_f32 v203, v203, v74, v75
	v_max3_f32 v203, v203, v76, v77
	v_max3_f32 v203, v203, v78, v79
	v_max3_f32 v204, v203, v80, v81
	v_mov_b32_e32 v205, v204
	s_nop 1
	v_permlane32_swap_b32_e32 v204, v205
	s_waitcnt lgkmcnt(0)
	v_max_f32_e32 v204, v204, v205
	v_mul_f32_e32 v204, 0x3e38aa3b, v204
	v_max_f32_e32 v205, v197, v197
	v_max_f32_e32 v219, v205, v204
	v_cmp_gt_f32_e32 vcc, v219, v197
	s_cbranch_vccz .LBB0_474
	v_sub_f32_e32 v197, v197, v219
	v_exp_f32_e32 v204, v197
	v_mov_b32_e32 v197, v219
	v_mul_f32_e32 v196, v196, v204
	v_pk_mul_f32 v[64:65], v[64:65], v[204:205] op_sel_hi:[1,0]
	v_pk_mul_f32 v[62:63], v[62:63], v[204:205] op_sel_hi:[1,0]
	v_pk_mul_f32 v[60:61], v[60:61], v[204:205] op_sel_hi:[1,0]
	v_pk_mul_f32 v[58:59], v[58:59], v[204:205] op_sel_hi:[1,0]
	v_pk_mul_f32 v[56:57], v[56:57], v[204:205] op_sel_hi:[1,0]
	v_pk_mul_f32 v[54:55], v[54:55], v[204:205] op_sel_hi:[1,0]
	v_pk_mul_f32 v[52:53], v[52:53], v[204:205] op_sel_hi:[1,0]
	v_pk_mul_f32 v[50:51], v[50:51], v[204:205] op_sel_hi:[1,0]
	v_pk_mul_f32 v[48:49], v[48:49], v[204:205] op_sel_hi:[1,0]
	v_pk_mul_f32 v[46:47], v[46:47], v[204:205] op_sel_hi:[1,0]
	v_pk_mul_f32 v[44:45], v[44:45], v[204:205] op_sel_hi:[1,0]
	v_pk_mul_f32 v[42:43], v[42:43], v[204:205] op_sel_hi:[1,0]
	v_pk_mul_f32 v[40:41], v[40:41], v[204:205] op_sel_hi:[1,0]
	v_pk_mul_f32 v[38:39], v[38:39], v[204:205] op_sel_hi:[1,0]
	v_pk_mul_f32 v[36:37], v[36:37], v[204:205] op_sel_hi:[1,0]
	v_pk_mul_f32 v[34:35], v[34:35], v[204:205] op_sel_hi:[1,0]

; __device__ __forceinline__ void attn_mfma(PP p, unsigned char* shm, int wv) {
;     ...
;                     float mx = s[0];
; #pragma unroll
;                     for (int i = 1; i < 16; ++i) mx = fmaxf(mx, s[i]);
;                     mx = fmaxf(mx, __shfl_xor(mx, 32));
;                     const float mnew = fmaxf(mrun[qi], mx * SC2);
;                     if (__builtin_amdgcn_ballot_w64(mnew > mrun[qi]) != 0ull) {
;                         const float alpha = __builtin_amdgcn_exp2f(mrun[qi] - mnew);
;                         lrun[qi] *= alpha;
; #pragma unroll
;                         for (int db = 0; db < 2; ++db)
; #pragma unroll
;                             for (int i = 0; i < 16; ++i) oacc[db][qi][i] *= alpha;
;                         mrun[qi] = mnew;
;                     }
.LBB0_485:
	s_nop 3
	v_max_f32_e32 v146, v67, v67
	v_max_f32_e32 v147, v66, v66
	v_max_f32_e32 v146, v147, v146
	v_max3_f32 v146, v146, v68, v69
	v_max3_f32 v146, v146, v70, v71
	v_max3_f32 v146, v146, v72, v73
	v_max3_f32 v146, v146, v74, v75
	v_max3_f32 v146, v146, v76, v77
	v_max3_f32 v146, v146, v78, v79
	v_max3_f32 v146, v146, v80, v81
	v_mov_b32_e32 v147, v146
	s_nop 1
	v_permlane32_swap_b32_e32 v146, v147
	s_waitcnt lgkmcnt(0)
	v_max_f32_e32 v146, v146, v147
	v_mul_f32_e32 v146, 0x3e38aa3b, v146
	v_max_f32_e32 v147, v198, v198
	v_max_f32_e32 v146, v147, v146
	v_cmp_gt_f32_e32 vcc, v146, v198
	s_cbranch_vccz .LBB0_462
	v_sub_f32_e32 v147, v198, v146
	v_exp_f32_e32 v148, v147
	v_mov_b32_e32 v198, v146
	v_mul_f32_e32 v1, v1, v148
	v_pk_mul_f32 v[32:33], v[32:33], v[148:149] op_sel_hi:[1,0]
	v_pk_mul_f32 v[30:31], v[30:31], v[148:149] op_sel_hi:[1,0]
	v_pk_mul_f32 v[28:29], v[28:29], v[148:149] op_sel_hi:[1,0]
	v_pk_mul_f32 v[26:27], v[26:27], v[148:149] op_sel_hi:[1,0]
	v_pk_mul_f32 v[24:25], v[24:25], v[148:149] op_sel_hi:[1,0]
	v_pk_mul_f32 v[22:23], v[22:23], v[148:149] op_sel_hi:[1,0]
	v_pk_mul_f32 v[20:21], v[20:21], v[148:149] op_sel_hi:[1,0]
	v_pk_mul_f32 v[18:19], v[18:19], v[148:149] op_sel_hi:[1,0]
	v_pk_mul_f32 v[16:17], v[16:17], v[148:149] op_sel_hi:[1,0]
	v_pk_mul_f32 v[14:15], v[14:15], v[148:149] op_sel_hi:[1,0]
	v_pk_mul_f32 v[12:13], v[12:13], v[148:149] op_sel_hi:[1,0]
	v_pk_mul_f32 v[10:11], v[10:11], v[148:149] op_sel_hi:[1,0]
	v_pk_mul_f32 v[8:9], v[8:9], v[148:149] op_sel_hi:[1,0]
	v_pk_mul_f32 v[6:7], v[6:7], v[148:149] op_sel_hi:[1,0]
	v_pk_mul_f32 v[4:5], v[4:5], v[148:149] op_sel_hi:[1,0]
	v_pk_mul_f32 v[2:3], v[2:3], v[148:149] op_sel_hi:[1,0]
	s_branch .LBB0_462
